# local barriers: L1 invalidate issued by wave 1 in parallel with wave 0 flag store and poll
# speedup vs baseline: 1.0006x; 1.0006x over previous
.LBB0_125:
	s_cmp_gt_i32 s69, 2
	s_cselect_b64 s[0:1], -1, 0
	s_and_b64 s[2:3], s[4:5], s[0:1]
	s_andn2_b64 vcc, exec, s[2:3]
	s_cbranch_vccnz .LBB0_179
	s_waitcnt vmcnt(0)
	s_waitcnt lgkmcnt(0)
	s_barrier
	v_mov_b32_e32 v0, 0x20040
	ds_read_b32 v2, v0
	ds_read_b32 v3, v0 offset:16
	ds_read_b32 v5, v0 offset:8
	s_lshl_b32 s2, s33, 7
	s_add_u32 s2, s2, 0x3600
	v_lshl_add_u32 v0, v199, 2, s2
	v_mov_b32_e32 v6, 1
	s_waitcnt lgkmcnt(0)
	v_cmp_eq_u32_e32 vcc, 0, v3
	s_cbranch_vccnz .Lxl_orig_1
	v_cmp_lt_u32_e32 vcc, 32, v2
	s_cbranch_vccnz .Lxl_orig_1
	v_lshl_add_u32 v1, v5, 2, s2
	v_readfirstlane_b32 s3, v199
	s_nop 3
	s_cmp_eq_u32 s3, 64
	s_cbranch_scc0 .Lxl_noinv_1
	buffer_inv sc1
	s_waitcnt vmcnt(0)
.Lxl_noinv_1:
	v_cmp_lt_u32_e32 vcc, v199, v2
	s_and_saveexec_b64 s[4:5], vcc
	s_cbranch_execz .LBB0_178
	v_cmp_eq_u32_e32 vcc, 0, v199
	s_and_saveexec_b64 s[2:3], vcc
	global_store_dword v1, v6, s[92:93]
	s_mov_b64 exec, s[2:3]
	s_mov_b32 s2, 0x20000

.LBB0_262:
	s_cmp_gt_i32 s69, 3
	s_cselect_b64 s[0:1], -1, 0
	s_and_b64 s[2:3], s[4:5], s[0:1]
	s_andn2_b64 vcc, exec, s[2:3]
	s_cbranch_vccnz .LBB0_316
	s_waitcnt vmcnt(0)
	s_waitcnt vmcnt(0) lgkmcnt(0)
	s_barrier
	v_mov_b32_e32 v0, 0x20040
	ds_read_b32 v2, v0
	ds_read_b32 v3, v0 offset:16
	ds_read_b32 v5, v0 offset:8
	s_lshl_b32 s2, s33, 7
	s_add_u32 s2, s2, 0x3600
	v_lshl_add_u32 v0, v199, 2, s2
	v_mov_b32_e32 v6, 2
	s_waitcnt lgkmcnt(0)
	v_cmp_eq_u32_e32 vcc, 0, v3
	s_cbranch_vccnz .Lxl_orig_2
	v_cmp_lt_u32_e32 vcc, 32, v2
	s_cbranch_vccnz .Lxl_orig_2
	v_lshl_add_u32 v1, v5, 2, s2
	v_readfirstlane_b32 s3, v199
	s_nop 3
	s_cmp_eq_u32 s3, 64
	s_cbranch_scc0 .Lxl_noinv_2
	buffer_inv sc1
	s_waitcnt vmcnt(0)

.LBB0_363:
	s_cmp_gt_i32 s69, 4
	s_cselect_b64 s[0:1], -1, 0
	s_and_b64 s[2:3], s[8:9], s[0:1]
	s_andn2_b64 vcc, exec, s[2:3]
	s_cbranch_vccnz .LBB0_417
	s_waitcnt vmcnt(0)
	s_waitcnt vmcnt(0) lgkmcnt(0)
	s_barrier
	v_mov_b32_e32 v0, 0x20040
	ds_read_b32 v2, v0
	ds_read_b32 v3, v0 offset:16
	ds_read_b32 v5, v0 offset:8
	s_lshl_b32 s2, s33, 7
	s_add_u32 s2, s2, 0x3600
	v_lshl_add_u32 v0, v199, 2, s2
	v_mov_b32_e32 v6, 3
	s_waitcnt lgkmcnt(0)
	v_cmp_eq_u32_e32 vcc, 0, v3
	s_cbranch_vccnz .Lxl_orig_3
	v_cmp_lt_u32_e32 vcc, 32, v2
	s_cbranch_vccnz .Lxl_orig_3
	v_lshl_add_u32 v1, v5, 2, s2
	v_readfirstlane_b32 s3, v199
	s_nop 3
	s_cmp_eq_u32 s3, 64
	s_cbranch_scc0 .Lxl_noinv_3
	buffer_inv sc1
	s_waitcnt vmcnt(0)

.LBB0_1502:
	s_cmp_gt_i32 s69, 7
	s_cselect_b64 s[2:3], -1, 0
	s_and_b64 s[0:1], s[0:1], s[2:3]
	s_andn2_b64 vcc, exec, s[0:1]
	s_cbranch_vccnz .LBB0_1556
	s_waitcnt vmcnt(0)
	s_waitcnt vmcnt(0) lgkmcnt(0)
	s_barrier
	v_mov_b32_e32 v0, 0x20040
	ds_read_b32 v2, v0
	ds_read_b32 v3, v0 offset:16
	ds_read_b32 v5, v0 offset:8
	s_lshl_b32 s4, s33, 7
	s_add_u32 s4, s4, 0x3600
	v_lshl_add_u32 v0, v199, 2, s4
	v_mov_b32_e32 v6, 4
	s_waitcnt lgkmcnt(0)
	v_cmp_eq_u32_e32 vcc, 0, v3
	s_cbranch_vccnz .Lxl_orig_6
	v_cmp_lt_u32_e32 vcc, 32, v2
	s_cbranch_vccnz .Lxl_orig_6
	v_lshl_add_u32 v1, v5, 2, s4
	v_readfirstlane_b32 s5, v199
	s_nop 3
	s_cmp_eq_u32 s5, 64
	s_cbranch_scc0 .Lxl_noinv_6
	buffer_inv sc1
	s_waitcnt vmcnt(0)
.Lxl_noinv_6:
	v_cmp_lt_u32_e32 vcc, v199, v2
	s_and_saveexec_b64 s[0:1], vcc
	s_cbranch_execz .LBB0_1555
	v_cmp_eq_u32_e32 vcc, 0, v199
	s_and_saveexec_b64 s[4:5], vcc
	global_store_dword v1, v6, s[92:93]
	s_mov_b64 exec, s[4:5]
	s_mov_b32 s4, 0x20000

.LBB0_1599:
	s_cmp_gt_i32 s69, 8
	s_cselect_b64 s[2:3], -1, 0
	s_and_b64 s[0:1], s[0:1], s[2:3]
	v_readlane_b32 s60, v255, 20
	s_andn2_b64 vcc, exec, s[0:1]
	v_readlane_b32 s61, v255, 21
	s_cbranch_vccnz .LBB0_1653
	s_waitcnt vmcnt(0)
	s_waitcnt vmcnt(0) lgkmcnt(0)
	s_barrier
	v_mov_b32_e32 v0, 0x20040
	ds_read_b32 v2, v0
	ds_read_b32 v3, v0 offset:16
	ds_read_b32 v5, v0 offset:8
	s_lshl_b32 s4, s33, 7
	s_add_u32 s4, s4, 0x3600
	v_lshl_add_u32 v0, v199, 2, s4
	v_mov_b32_e32 v6, 5
	s_waitcnt lgkmcnt(0)
	v_cmp_eq_u32_e32 vcc, 0, v3
	s_cbranch_vccnz .Lxl_orig_7
	v_cmp_lt_u32_e32 vcc, 32, v2
	s_cbranch_vccnz .Lxl_orig_7
	v_lshl_add_u32 v1, v5, 2, s4
	v_readfirstlane_b32 s5, v199
	s_nop 3
	s_cmp_eq_u32 s5, 64
	s_cbranch_scc0 .Lxl_noinv_7
	buffer_inv sc1
	s_waitcnt vmcnt(0)

.LBB0_1710:
	s_cmp_gt_i32 s69, 9
	s_cselect_b64 s[0:1], -1, 0
	s_and_b64 s[2:3], s[6:7], s[0:1]
	s_andn2_b64 vcc, exec, s[2:3]
	s_cbranch_vccnz .LBB0_1764
	s_waitcnt vmcnt(0)
	s_waitcnt vmcnt(0) lgkmcnt(0)
	s_barrier
	v_mov_b32_e32 v0, 0x20040
	ds_read_b32 v2, v0
	ds_read_b32 v3, v0 offset:16
	ds_read_b32 v5, v0 offset:8
	s_lshl_b32 s4, s33, 7
	s_add_u32 s4, s4, 0x3600
	v_lshl_add_u32 v0, v199, 2, s4
	v_mov_b32_e32 v6, 6
	s_waitcnt lgkmcnt(0)
	v_cmp_eq_u32_e32 vcc, 0, v3
	s_cbranch_vccnz .Lxl_orig_8
	v_cmp_lt_u32_e32 vcc, 32, v2
	s_cbranch_vccnz .Lxl_orig_8
	v_lshl_add_u32 v1, v5, 2, s4
	v_readfirstlane_b32 s5, v199
	s_nop 3
	s_cmp_eq_u32 s5, 64
	s_cbranch_scc0 .Lxl_noinv_8
	buffer_inv sc1
	s_waitcnt vmcnt(0)
.Lxl_noinv_8:
	v_cmp_lt_u32_e32 vcc, v199, v2
	s_and_saveexec_b64 s[2:3], vcc
	s_cbranch_execz .LBB0_1763
	v_cmp_eq_u32_e32 vcc, 0, v199
	s_and_saveexec_b64 s[4:5], vcc
	global_store_dword v1, v6, s[92:93]
	s_mov_b64 exec, s[4:5]
	s_mov_b32 s4, 0x20000
